# v2 + static s_setprio 1 for waves 4-7 inside the NSA item loop
# speedup vs baseline: 1.0026x; 1.0026x over previous
; __device__ __forceinline__ int tid_() { int t = threadIdx.x; asm volatile("" : "+v"(t)); return t; }
; #define LAS __attribute__((address_space(3)))
;     unsigned* ctr = (unsigned*)(a->ws + WS_CTL) + 64 * (l + 2 * rep);
;     for (;;) {
;         __syncthreads();
;         if (tid_() == 0) *(LAS int*)(lds + NSA_ITEM) = (int)atomicAdd(ctr, 1u);
;         __syncthreads();
;         const int it = *(LAS int*)(lds + NSA_ITEM);
;         if (it >= 1024) break;
;         nsa_item(a, lds, it);
;     }
; }
.LBB0_599:
	s_load_dwordx2 s[0:1], s[12:13], 0x120
	s_waitcnt lgkmcnt(0)
	s_add_u32 s2, s0, s10
	s_addc_u32 s3, s1, s11
	v_writelane_b32 v254, s2, 37
	s_nop 1
	v_writelane_b32 v254, s3, 38
	s_add_u32 s2, s0, 0x8000000
	s_addc_u32 s3, s1, 0
	v_writelane_b32 v254, s2, 39
	s_nop 1
	v_writelane_b32 v254, s3, 40
	s_add_u32 s2, s0, 0x180000
	v_writelane_b32 v254, s2, 41
	s_addc_u32 s2, s1, 0
	v_writelane_b32 v254, s2, 42
	s_add_u32 s2, s0, 0x200000
	v_writelane_b32 v254, s2, 43
	v_writelane_b32 v254, s0, 44
	s_nop 1
	v_writelane_b32 v254, s1, 45
	s_addc_u32 s0, s1, 0
	v_writelane_b32 v254, s0, 46
	v_readfirstlane_b32 s100, v232
	s_nop 3
	s_lshr_b32 s100, s100, 6
	s_cmp_ge_u32 s100, 4
	s_cbranch_scc0 .Lnsa_prio_skip
	s_setprio 1
.Lnsa_prio_skip:
	s_branch .LBB0_603

; __device__ __forceinline__ void xcd_barrier(const XcdBarrier& b) {
;     asm volatile("s_waitcnt vmcnt(0)" ::: "memory");
;     __syncthreads();
;     if (threadIdx.x == 0) {
;         unsigned* bar = b.bar;
;         __builtin_amdgcn_s_waitcnt(0);
;         unsigned nloc = b.st[0], nx = b.st[1];
;         if (nloc == 0u) { xcd_barrier_complete(bar, b.x, nloc, nx); b.st[0] = nloc; b.st[1] = nx; }
.LBB0_926:
	s_setprio 0
	s_waitcnt vmcnt(0)
	s_barrier
	s_mov_b64 s[0:1], exec
	v_readlane_b32 s2, v252, 4
	v_readlane_b32 s3, v252, 5
	s_and_b64 s[2:3], s[0:1], s[2:3]
	s_mov_b64 exec, s[2:3]
	s_cbranch_execz .LBB0_978
	v_readlane_b32 s2, v254, 4
	s_waitcnt vmcnt(0) expcnt(0) lgkmcnt(0)
	s_nop 0
	v_mov_b32_e32 v0, s2
	ds_read_b32 v2, v0
	v_readlane_b32 s2, v254, 5
	s_waitcnt lgkmcnt(0)
	v_cmp_ne_u32_e32 vcc, 0, v2
	v_mov_b32_e32 v0, s2
	ds_read_b32 v0, v0
	s_cbranch_vccnz .LBB0_942
	s_mov_b32 s8, 1
	s_branch .LBB0_930
